# baseline (speedup 1.0000x reference)
.LBB0_371:
	s_waitcnt lgkmcnt(8)
	ds_read_b64_tr_b16 v[140:141], v213 offset:1024
	ds_read_b64_tr_b16 v[142:143], v213 offset:5120
	ds_read_b64_tr_b16 v[144:145], v213 offset:9216
	ds_read_b64_tr_b16 v[146:147], v213 offset:13312
	v_mfma_f32_16x16x32_bf16 v[60:63], v[120:123], v[128:131], v[60:63]
	v_max_i32_e32 v160, v84, v85
	v_max3_i32 v161, v87, v96, v97
	v_max3_i32 v160, v160, v86, v98
	v_max3_i32 v161, v161, v100, v101
	v_mfma_f32_16x16x32_bf16 v[64:67], v[124:127], v[128:131], v[64:67]
	v_max3_i32 v160, v160, v99, v102
	v_max3_i32 v161, v161, v108, v109
	v_max3_i32 v160, v160, v103, v110
	v_max3_i32 v162, v160, v111, v161
	v_mfma_f32_16x16x32_bf16 v[60:63], v[112:115], v[132:135], v[60:63]
	v_max_i32_e32 v160, v80, v81
	v_max3_i32 v161, v83, v88, v89
	v_max3_i32 v160, v160, v82, v90
	v_max3_i32 v161, v161, v92, v93
	v_mfma_f32_16x16x32_bf16 v[64:67], v[116:119], v[132:135], v[64:67]
	v_max3_i32 v160, v160, v91, v94
	v_max3_i32 v161, v161, v104, v105
	v_max3_i32 v160, v160, v95, v106
	v_max3_i32 v160, v160, v107, v161
	v_max_f32_e32 v164, v162, v160
	v_cmp_ge_f32_e32 vcc, s3, v164
	s_cmp_lg_u64 vcc, exec
	s_cselect_b64 s[12:13], -1, 0
	v_mov_b32_e32 v239, 1.0
	s_cbranch_scc1 .LBB0_383
	v_mov_b32_e32 v238, 1.0

.LBB0_376:
	s_waitcnt lgkmcnt(8)
	ds_read_b64_tr_b16 v[140:141], v215 offset:1024
	ds_read_b64_tr_b16 v[142:143], v215 offset:5120
	ds_read_b64_tr_b16 v[144:145], v215 offset:9216
	ds_read_b64_tr_b16 v[146:147], v215 offset:13312
	v_mfma_f32_16x16x32_bf16 v[60:63], v[120:123], v[168:171], v[60:63]
	v_max_i32_e32 v240, v84, v85
	v_max3_i32 v241, v87, v96, v97
	v_max3_i32 v240, v240, v86, v98
	v_max3_i32 v241, v241, v100, v101
	v_mfma_f32_16x16x32_bf16 v[64:67], v[124:127], v[168:171], v[64:67]
	v_max3_i32 v240, v240, v99, v102
	v_max3_i32 v241, v241, v108, v109
	v_max3_i32 v240, v240, v103, v110
	v_max3_i32 v242, v240, v111, v241
	v_mfma_f32_16x16x32_bf16 v[60:63], v[112:115], v[172:175], v[60:63]
	v_max_i32_e32 v240, v80, v81
	v_max3_i32 v241, v83, v88, v89
	v_max3_i32 v240, v240, v82, v90
	v_max3_i32 v241, v241, v92, v93
	v_mfma_f32_16x16x32_bf16 v[64:67], v[116:119], v[172:175], v[64:67]
	v_max3_i32 v240, v240, v91, v94
	v_max3_i32 v241, v241, v104, v105
	v_max3_i32 v240, v240, v95, v106
	v_max3_i32 v241, v240, v107, v241
	v_max_f32_e32 v212, v242, v241
	v_cmp_ge_f32_e32 vcc, s3, v212
	s_cmp_lg_u64 vcc, exec
	s_cselect_b64 s[6:7], -1, 0
	s_cbranch_scc1 .LBB0_388
	v_mov_b32_e32 v249, 1.0
	v_mov_b32_e32 v248, 1.0

.LBB0_383:
	v_max_f32_e32 v161, v160, v160
	v_max_f32_e32 v163, v162, v162
	ds_bpermute_b32 v72, v217, v162
	s_waitcnt lgkmcnt(0)
	v_max_f32_e32 v72, v72, v72
	v_max_f32_e32 v72, v163, v72
	ds_bpermute_b32 v73, v216, v72
	s_waitcnt lgkmcnt(0)
	v_max3_f32 v76, v72, v73, 0
	ds_bpermute_b32 v72, v217, v160
	v_exp_f32_e64 v238, -v76
	v_sub_f32_e32 v87, v87, v76
	v_sub_f32_e32 v86, v86, v76
	v_sub_f32_e32 v85, v85, v76
	s_waitcnt lgkmcnt(0)
	v_max_f32_e32 v72, v72, v72
	v_max_f32_e32 v72, v161, v72
	ds_bpermute_b32 v73, v216, v72
	v_sub_f32_e32 v84, v84, v76
	v_sub_f32_e32 v99, v99, v76
	v_sub_f32_e32 v98, v98, v76
	v_sub_f32_e32 v97, v97, v76
	s_waitcnt lgkmcnt(0)
	v_max3_f32 v77, v72, v73, 0
	v_exp_f32_e64 v239, -v77
	v_pk_add_f32 v[208:209], v[208:209], v[76:77]
	v_sub_f32_e32 v96, v96, v76
	v_sub_f32_e32 v103, v103, v76
	v_sub_f32_e32 v102, v102, v76
	v_sub_f32_e32 v101, v101, v76
	v_sub_f32_e32 v100, v100, v76
	v_sub_f32_e32 v111, v111, v76
	v_sub_f32_e32 v110, v110, v76
	v_sub_f32_e32 v109, v109, v76
	v_sub_f32_e32 v108, v108, v76
	v_xor_b32_e32 v72, 0x80000000, v208
	v_xor_b32_e32 v76, 0x80000000, v209
	v_mov_b32_e32 v73, v72
	v_mov_b32_e32 v74, v72
	v_mov_b32_e32 v75, v72
	v_sub_f32_e32 v83, v83, v77
	v_sub_f32_e32 v82, v82, v77
	v_sub_f32_e32 v81, v81, v77
	v_sub_f32_e32 v80, v80, v77
	v_sub_f32_e32 v91, v91, v77
	v_sub_f32_e32 v90, v90, v77
	v_sub_f32_e32 v89, v89, v77
	v_sub_f32_e32 v88, v88, v77
	v_sub_f32_e32 v95, v95, v77
	v_sub_f32_e32 v94, v94, v77
	v_sub_f32_e32 v93, v93, v77
	v_sub_f32_e32 v92, v92, v77
	v_sub_f32_e32 v107, v107, v77
	v_sub_f32_e32 v106, v106, v77
	v_sub_f32_e32 v105, v105, v77
	v_sub_f32_e32 v104, v104, v77
	v_mov_b32_e32 v77, v76
	v_mov_b32_e32 v78, v76
	v_mov_b32_e32 v79, v76
	s_branch .LBB0_373

.LBB0_388:
	v_max_f32_e32 v240, v241, v241
	v_max_f32_e32 v243, v242, v242
	v_mov_b32_e32 v249, 1.0
	s_branch .LBB0_378

.LBB0_398:
	s_waitcnt lgkmcnt(8)
	ds_read_b64_tr_b16 v[140:141], v213 offset:1024
	ds_read_b64_tr_b16 v[142:143], v213 offset:5120
	ds_read_b64_tr_b16 v[144:145], v213 offset:9216
	ds_read_b64_tr_b16 v[146:147], v213 offset:13312
	v_mfma_f32_16x16x32_bf16 v[60:63], v[120:123], v[128:131], v[60:63]
	v_max_i32_e32 v160, v84, v85
	v_max3_i32 v161, v87, v96, v97
	v_max3_i32 v160, v160, v86, v98
	v_max3_i32 v161, v161, v100, v101
	v_mfma_f32_16x16x32_bf16 v[64:67], v[124:127], v[128:131], v[64:67]
	v_max3_i32 v160, v160, v99, v102
	v_max3_i32 v161, v161, v108, v109
	v_max3_i32 v160, v160, v103, v110
	v_max3_i32 v162, v160, v111, v161
	v_mfma_f32_16x16x32_bf16 v[60:63], v[112:115], v[132:135], v[60:63]
	v_max_i32_e32 v160, v80, v81
	v_max3_i32 v161, v83, v88, v89
	v_max3_i32 v160, v160, v82, v90
	v_max3_i32 v161, v161, v92, v93
	v_mfma_f32_16x16x32_bf16 v[64:67], v[116:119], v[132:135], v[64:67]
	v_max3_i32 v160, v160, v91, v94
	v_max3_i32 v161, v161, v104, v105
	v_max3_i32 v160, v160, v95, v106
	v_max3_i32 v160, v160, v107, v161
	v_max_f32_e32 v164, v162, v160
	v_cmp_ge_f32_e32 vcc, s3, v164
	s_cmp_lg_u64 vcc, exec
	s_cselect_b64 s[10:11], -1, 0
	v_mov_b32_e32 v239, 1.0
	s_cbranch_scc1 .LBB0_410
	v_mov_b32_e32 v238, 1.0

.LBB0_403:
	s_waitcnt lgkmcnt(8)
	ds_read_b64_tr_b16 v[140:141], v215 offset:1024
	ds_read_b64_tr_b16 v[142:143], v215 offset:5120
	ds_read_b64_tr_b16 v[144:145], v215 offset:9216
	ds_read_b64_tr_b16 v[146:147], v215 offset:13312
	v_mfma_f32_16x16x32_bf16 v[60:63], v[120:123], v[168:171], v[60:63]
	v_max_i32_e32 v212, v84, v85
	v_max3_i32 v213, v87, v96, v97
	v_max3_i32 v212, v212, v86, v98
	v_max3_i32 v213, v213, v100, v101
	v_mfma_f32_16x16x32_bf16 v[64:67], v[124:127], v[168:171], v[64:67]
	v_max3_i32 v212, v212, v99, v102
	v_max3_i32 v213, v213, v108, v109
	v_max3_i32 v212, v212, v103, v110
	v_max3_i32 v242, v212, v111, v213
	v_mfma_f32_16x16x32_bf16 v[60:63], v[112:115], v[172:175], v[60:63]
	v_max_i32_e32 v212, v80, v81
	v_max3_i32 v213, v83, v88, v89
	v_max3_i32 v212, v212, v82, v90
	v_max3_i32 v213, v213, v92, v93
	v_mfma_f32_16x16x32_bf16 v[64:67], v[116:119], v[172:175], v[64:67]
	v_max3_i32 v212, v212, v91, v94
	v_max3_i32 v213, v213, v104, v105
	v_max3_i32 v212, v212, v95, v106
	v_max3_i32 v241, v212, v107, v213
	v_max_f32_e32 v212, v242, v241
	v_cmp_ge_f32_e32 vcc, s3, v212
	s_cmp_lg_u64 vcc, exec
	s_cselect_b64 s[6:7], -1, 0
	s_cbranch_scc1 .LBB0_415
	v_mov_b32_e32 v249, 1.0
	v_mov_b32_e32 v248, 1.0
